# P4 task-table cost weights NSA:DSA 13:12
# baseline (speedup 1.0000x reference)
; __global__ void __launch_bounds__(NTHR, 2) fwd_kernel(Args a) {
;     ...
;         if (gw == NGW - 1 - 256 || (NGW <= 256 && gw == 0)) {
;             for (int k = lane; k < 96; k += 64) {
;                 const int cost = k < 32 ? 7 * ((k + 1) + (k + 1 < 9 ? k + 1 : 9)) : 6 * (((k - 32) >> 1) + 1), cnt = k < 32 ? 32 : 16; int pos = 0;
;                 for (int k2 = 0; k2 < 96; ++k2) { const int c2 = k2 < 32 ? 7 * ((k2 + 1) + (k2 + 1 < 9 ? k2 + 1 : 9)) : 6 * (((k2 - 32) >> 1) + 1), n2 = k2 < 32 ? 32 : 16;
;                     if (c2 > cost || (c2 == cost && k2 < k)) pos += n2; }
;                 for (int bb = 0; bb < cnt; ++bb) TASKTAB[pos + bb] = (unsigned)k | ((unsigned)bb << 8);
;             }
;         }
.LBB0_159:
	v_cmp_lt_u32_e32 vcc, 31, v2
	s_and_saveexec_b64 s[4:5], vcc
	s_xor_b64 s[4:5], exec, s[4:5]
	v_subrev_u32_e32 v1, 32, v2
	v_lshrrev_b32_e32 v1, 1, v1
	v_mad_u64_u32 v[4:5], s[6:7], v1, 12, 12
	s_or_saveexec_b64 s[4:5], s[4:5]
	v_mov_b32_e32 v6, 16
	s_xor_b64 exec, exec, s[4:5]
	v_add_u32_e32 v1, 1, v2
	v_min_u32_e32 v3, 9, v1
	v_add_u32_e32 v1, v3, v1
	v_mul_lo_u32 v4, v1, 13
	v_mov_b32_e32 v6, 32
	s_or_b64 exec, exec, s[4:5]
	s_and_b64 s[4:5], exec, vcc
	s_or_b64 s[22:23], s[4:5], s[22:23]
	v_mov_b32_e32 v3, v4
	v_mov_b32_e32 v1, v2
	s_mov_b32 s21, 1
	v_mov_b32_e32 v7, 0
	s_movk_i32 s30, 0x60
	s_mov_b32 s31, 0
	v_mov_b32_e32 v5, 0
.LBB0_164:
	s_sub_i32 s6, s31, 32
	s_sub_i32 s7, s21, 32
	s_add_i32 s8, s21, 1
	s_add_i32 s9, s31, 1
	s_lshr_b32 s7, s7, 1
	s_lshr_b32 s6, s6, 1
	s_min_u32 s10, s9, 9
	s_min_u32 s11, s8, 9
	s_mul_i32 s6, s6, 12
	s_mul_i32 s7, s7, 12
	s_add_i32 s8, s11, s8
	s_add_i32 s9, s10, s9
	s_add_i32 s7, s7, 12
	s_add_i32 s6, s6, 12
	s_mul_i32 s9, s9, 13
	s_cmp_lt_u32 s31, 32
	s_mul_i32 s8, s8, 13
	s_cselect_b32 s10, 32, 16
	s_cselect_b32 s9, s9, s6
	s_cmp_lt_u32 s21, 32
	v_cmp_ge_u32_e32 vcc, s31, v2
	s_cselect_b32 s12, s8, s7
	v_cmp_le_i32_e64 s[6:7], s9, v4
	v_cmp_ne_u32_e64 s[8:9], s9, v4
	s_cselect_b32 s33, 32, 16
	s_sub_i32 s40, s21, 30
	s_sub_i32 s41, s31, 30
	s_or_b64 s[34:35], s[8:9], vcc
	v_cmp_ge_u32_e64 s[4:5], s21, v1
	v_mov_b32_e32 v8, s10
	s_add_i32 s46, s31, 3
	s_add_i32 s47, s21, 3
	v_cmp_le_i32_e64 s[10:11], s12, v3
	v_cmp_ne_u32_e64 s[12:13], s12, v3
	v_mov_b32_e32 v9, s33
	s_lshr_b32 s33, s41, 1
	s_lshr_b32 s40, s40, 1
	s_and_b64 s[6:7], s[6:7], s[34:35]
	s_min_u32 s41, s47, 9
	s_min_u32 s48, s46, 9
	s_or_b64 s[4:5], s[12:13], s[4:5]
	v_cndmask_b32_e64 v8, v8, 0, s[6:7]
	s_mul_i32 s6, s40, 12
	s_mul_i32 s7, s33, 12
	s_add_i32 s36, s31, 2
	s_add_i32 s37, s21, 2
	s_add_i32 s12, s48, s46
	s_add_i32 s13, s41, s47
	s_and_b64 s[4:5], s[10:11], s[4:5]
	s_add_i32 s7, s7, 12
	s_add_i32 s6, s6, 12
	s_mul_i32 s13, s13, 13
	s_cmp_lt_u32 s37, 32
	s_mul_i32 s12, s12, 13
	s_cselect_b32 s10, 32, 16
	s_cselect_b32 s6, s13, s6
	s_cmp_lt_u32 s36, 32
	v_cmp_ge_u32_e32 vcc, s37, v1
	v_cndmask_b32_e64 v9, v9, 0, s[4:5]
	s_cselect_b32 s33, 32, 16
	s_cselect_b32 s12, s12, s7
	v_cmp_le_i32_e64 s[4:5], s6, v3
	v_cmp_ne_u32_e64 s[6:7], s6, v3
	s_sub_i32 s40, s21, 28
	s_sub_i32 s41, s31, 28
	v_cmp_ge_u32_e64 s[8:9], s36, v2
	v_add_u32_e32 v7, v7, v8
	v_add_u32_e32 v5, v5, v9
	v_mov_b32_e32 v8, s10
	s_add_i32 s46, s31, 5
	s_add_i32 s47, s21, 5
	v_cmp_le_i32_e64 s[10:11], s12, v4
	v_cmp_ne_u32_e64 s[12:13], s12, v4
	s_or_b64 s[34:35], s[6:7], vcc
	v_mov_b32_e32 v9, s33
	s_lshr_b32 s33, s41, 1
	s_lshr_b32 s40, s40, 1
	s_min_u32 s41, s47, 9
	s_min_u32 s48, s46, 9
	s_or_b64 s[8:9], s[12:13], s[8:9]
	s_and_b64 s[4:5], s[4:5], s[34:35]
	s_mul_i32 s12, s40, 12
	s_mul_i32 s13, s33, 12
	s_add_i32 s36, s31, 4
	s_add_i32 s37, s21, 4
	v_cndmask_b32_e64 v8, v8, 0, s[4:5]
	s_add_i32 s33, s48, s46
	s_add_i32 s34, s41, s47
	s_and_b64 s[4:5], s[10:11], s[8:9]
	s_add_i32 s13, s13, 12
	s_add_i32 s12, s12, 12
	s_mul_i32 s34, s34, 13
	s_cmp_lt_u32 s37, 32
	s_mul_i32 s33, s33, 13
	s_cselect_b32 s10, 32, 16
	s_cselect_b32 s8, s34, s12
	s_cmp_lt_u32 s36, 32
	v_cmp_ge_u32_e32 vcc, s37, v1
	v_cndmask_b32_e64 v9, v9, 0, s[4:5]
	s_cselect_b32 s12, s33, s13
	v_cmp_le_i32_e64 s[4:5], s8, v3
	v_cmp_ne_u32_e64 s[8:9], s8, v3
	v_cmp_ge_u32_e64 s[6:7], s36, v2
	s_cselect_b32 s34, 32, 16
	v_mov_b32_e32 v10, s10
	v_cmp_le_i32_e64 s[10:11], s12, v4
	v_cmp_ne_u32_e64 s[12:13], s12, v4
	s_or_b64 s[8:9], s[8:9], vcc
	s_or_b64 s[6:7], s[12:13], s[6:7]
	s_and_b64 s[4:5], s[4:5], s[8:9]
	v_mov_b32_e32 v11, s34
	v_cndmask_b32_e64 v10, v10, 0, s[4:5]
	s_and_b64 s[4:5], s[10:11], s[6:7]
	s_add_i32 s31, s31, 6
	s_add_i32 s21, s21, 6
	s_add_i32 s30, s30, -6
	v_cndmask_b32_e64 v11, v11, 0, s[4:5]
	v_add3_u32 v5, v5, v8, v10
	s_cmp_lg_u32 s30, 0
	v_add3_u32 v7, v7, v9, v11
	s_cbranch_scc1 .LBB0_164
	v_add_u32_e32 v4, v7, v5
	v_ashrrev_i32_e32 v5, 31, v4
	v_lshl_add_u64 v[4:5], v[4:5], 2, s[42:43]
	s_mov_b32 s6, 1
	s_mov_b32 s7, 0
	s_mov_b64 s[4:5], 0
